# sample_outproj: 16 fragment loads of each 256-deep K step issued together with counted waits
# baseline (speedup 1.0000x reference)
; __device__ __forceinline__ void sample_outproj(const bf16_t* MIXp, const bf16_t* Wt, int K, const float* Xs  , float* Z, int gw, int NGW, int lane) {
;     ...
;     for (int task = gw; task < 16 * 64; task += NGW) {
;         const int rt = task >> 6, ct = task & 63;
;         const bf16_t* ap = MIXp + (size_t)(NP + rt * 16 + fr) * K + g4 * 8;
;         const bf16_t* bp = Wt + (size_t)(ct * 16 + fr) * K + g4 * 8;
;         f32x4 acc = (f32x4){0.f, 0.f, 0.f, 0.f};
; #pragma unroll 8
;         for (int ks = 0; ks < K / 32; ++ks) { const bf16x8 a = *(const bf16x8*)(ap + ks * 32), b = *(const bf16x8*)(bp + ks * 32);
;             acc = __builtin_amdgcn_mfma_f32_16x16x32_bf16(a, b, acc, 0, 0, 0); }
; #pragma unroll
;         for (int r = 0; r < 4; ++r) { const size_t os = (size_t)(rt * 16 + g4 * 4 + r) * DM + ct * 16 + fr; Z[(size_t)NP * DM + os] = Xs[os] * ALPHA + acc[r]; }
;     }
.LBB0_810:
	v_lshl_add_u64 v[16:17], v[10:11], 0, s[2:3]
	v_add_co_u32_e32 v24, vcc, 0x18a00000, v16
	v_lshl_add_u64 v[26:27], v[8:9], 0, s[2:3]
	s_nop 0
	v_addc_co_u32_e32 v25, vcc, 0, v17, vcc
	global_load_dwordx4 v[32:35], v[24:25], off
	global_load_dwordx4 v[64:67], v[26:27], off offset:-256
	global_load_dwordx4 v[36:39], v[24:25], off offset:64
	global_load_dwordx4 v[68:71], v[26:27], off offset:-192
	global_load_dwordx4 v[40:43], v[24:25], off offset:128
	global_load_dwordx4 v[72:75], v[26:27], off offset:-128
	global_load_dwordx4 v[44:47], v[24:25], off offset:192
	global_load_dwordx4 v[76:79], v[26:27], off offset:-64
	global_load_dwordx4 v[48:51], v[24:25], off offset:256
	global_load_dwordx4 v[80:83], v[26:27], off
	global_load_dwordx4 v[52:55], v[24:25], off offset:320
	global_load_dwordx4 v[84:87], v[26:27], off offset:64
	global_load_dwordx4 v[56:59], v[24:25], off offset:384
	global_load_dwordx4 v[88:91], v[26:27], off offset:128
	global_load_dwordx4 v[60:63], v[24:25], off offset:448
	global_load_dwordx4 v[92:95], v[26:27], off offset:192
	s_add_u32 s2, s2, 0x200
	s_addc_u32 s3, s3, 0
	s_cmpk_eq_i32 s2, 0x400
	s_waitcnt vmcnt(14)
	v_mfma_f32_16x16x32_bf16 v[0:3], v[32:35], v[64:67], v[0:3]
	s_waitcnt vmcnt(12)
	v_mfma_f32_16x16x32_bf16 v[0:3], v[36:39], v[68:71], v[0:3]
	s_waitcnt vmcnt(10)
	v_mfma_f32_16x16x32_bf16 v[0:3], v[40:43], v[72:75], v[0:3]
	s_waitcnt vmcnt(8)
	v_mfma_f32_16x16x32_bf16 v[0:3], v[44:47], v[76:79], v[0:3]
	s_waitcnt vmcnt(6)
	v_mfma_f32_16x16x32_bf16 v[0:3], v[48:51], v[80:83], v[0:3]
	s_waitcnt vmcnt(4)
	v_mfma_f32_16x16x32_bf16 v[0:3], v[52:55], v[84:87], v[0:3]
	s_waitcnt vmcnt(2)
	v_mfma_f32_16x16x32_bf16 v[0:3], v[56:59], v[88:91], v[0:3]
	s_waitcnt vmcnt(0)
	v_mfma_f32_16x16x32_bf16 v[0:3], v[60:63], v[92:95], v[0:3]
	s_cbranch_scc0 .LBB0_810
	s_lshl_b32 s2, s0, 4
	s_and_b32 s2, s2, 0x3f0
	v_add_u32_e32 v8, s7, v14
	v_or_b32_e32 v16, s2, v12
	v_ashrrev_i32_e32 v9, 31, v8
	v_lshlrev_b64 v[10:11], 12, v[8:9]
	v_lshlrev_b32_e32 v9, 2, v16
	v_or_b32_e32 v10, v10, v9
	v_lshl_add_u64 v[16:17], s[12:13], 0, v[10:11]
	global_load_dword v16, v[16:17], off
	v_readlane_b32 s2, v253, 8
	v_readlane_b32 s3, v253, 9
	s_brev_b32 s7, 32
	s_waitcnt vmcnt(0)
	v_fmamk_f32 v0, v16, 0x3fd744fd, v0
	v_lshl_add_u64 v[10:11], s[2:3], 0, v[10:11]
	v_add_co_u32_e32 v10, vcc, 0x4000000, v10
	s_nop 1
	v_addc_co_u32_e32 v11, vcc, 0, v11, vcc
	global_store_dword v[10:11], v0, off
	v_or_b32_e32 v10, 1, v8
	v_ashrrev_i32_e32 v11, 31, v10
	v_lshlrev_b64 v[10:11], 12, v[10:11]
	v_or_b32_e32 v10, v10, v9
	v_lshl_add_u64 v[16:17], s[12:13], 0, v[10:11]
	global_load_dword v0, v[16:17], off
	s_waitcnt vmcnt(0)
	v_fmamk_f32 v16, v0, 0x3fd744fd, v1
	v_lshl_add_u64 v[0:1], s[2:3], 0, v[10:11]
	v_add_co_u32_e32 v0, vcc, s7, v0
	s_nop 1
	v_addc_co_u32_e32 v1, vcc, 0, v1, vcc
	global_store_dword v[0:1], v16, off
	v_or_b32_e32 v0, 2, v8
	v_ashrrev_i32_e32 v1, 31, v0
	v_lshlrev_b64 v[0:1], 12, v[0:1]
	v_or_b32_e32 v0, v0, v9
	v_lshl_add_u64 v[10:11], s[12:13], 0, v[0:1]
	global_load_dword v10, v[10:11], off
	v_lshl_add_u64 v[0:1], s[2:3], 0, v[0:1]
	v_add_co_u32_e32 v0, vcc, s7, v0
	s_waitcnt vmcnt(0)
	v_fmamk_f32 v2, v10, 0x3fd744fd, v2
	v_addc_co_u32_e32 v1, vcc, 0, v1, vcc
	global_store_dword v[0:1], v2, off
	v_or_b32_e32 v0, 3, v8
	v_ashrrev_i32_e32 v1, 31, v0
	v_lshlrev_b64 v[0:1], 12, v[0:1]
	v_or_b32_e32 v0, v0, v9
	v_lshl_add_u64 v[8:9], s[12:13], 0, v[0:1]
	global_load_dword v2, v[8:9], off
	v_lshl_add_u64 v[0:1], s[2:3], 0, v[0:1]
	v_readlane_b32 s2, v255, 13
	s_add_i32 s0, s0, s2
	v_readlane_b32 s2, v254, 54
	v_add_co_u32_e32 v0, vcc, 0x4000000, v0
	s_add_i32 s5, s5, s2
	s_nop 0
	v_addc_co_u32_e32 v1, vcc, 0, v1, vcc
	s_cmpk_gt_i32 s0, 0x3ff
	v_readlane_b32 s3, v255, 14
	s_waitcnt vmcnt(0)
	v_fmac_f32_e32 v3, 0x3fd744fd, v2
	global_store_dword v[0:1], v3, off
	s_cbranch_scc0 .LBB0_809

; __device__ __forceinline__ void sample_outproj(const bf16_t* MIXp, const bf16_t* Wt, int K, const float* Xs  , float* Z, int gw, int NGW, int lane) {
;     ...
;     for (int task = gw; task < 16 * 64; task += NGW) {
;         const int rt = task >> 6, ct = task & 63;
;         const bf16_t* ap = MIXp + (size_t)(NP + rt * 16 + fr) * K + g4 * 8;
;         const bf16_t* bp = Wt + (size_t)(ct * 16 + fr) * K + g4 * 8;
;         f32x4 acc = (f32x4){0.f, 0.f, 0.f, 0.f};
; #pragma unroll 8
;         for (int ks = 0; ks < K / 32; ++ks) { const bf16x8 a = *(const bf16x8*)(ap + ks * 32), b = *(const bf16x8*)(bp + ks * 32);
;             acc = __builtin_amdgcn_mfma_f32_16x16x32_bf16(a, b, acc, 0, 0, 0); }
; #pragma unroll
;         for (int r = 0; r < 4; ++r) { const size_t os = (size_t)(rt * 16 + g4 * 4 + r) * DM + ct * 16 + fr; Z[(size_t)NP * DM + os] = Xs[os] * ALPHA + acc[r]; }
;     }
.LBB0_1563:
	v_lshl_add_u64 v[16:17], v[10:11], 0, s[24:25]
	v_add_co_u32_e32 v24, vcc, 0x18a00000, v16
	v_lshl_add_u64 v[26:27], v[8:9], 0, s[24:25]
	s_nop 0
	v_addc_co_u32_e32 v25, vcc, 0, v17, vcc
	global_load_dwordx4 v[32:35], v[24:25], off
	global_load_dwordx4 v[64:67], v[26:27], off offset:-256
	global_load_dwordx4 v[36:39], v[24:25], off offset:64
	global_load_dwordx4 v[68:71], v[26:27], off offset:-192
	global_load_dwordx4 v[40:43], v[24:25], off offset:128
	global_load_dwordx4 v[72:75], v[26:27], off offset:-128
	global_load_dwordx4 v[44:47], v[24:25], off offset:192
	global_load_dwordx4 v[76:79], v[26:27], off offset:-64
	global_load_dwordx4 v[48:51], v[24:25], off offset:256
	global_load_dwordx4 v[80:83], v[26:27], off
	global_load_dwordx4 v[52:55], v[24:25], off offset:320
	global_load_dwordx4 v[84:87], v[26:27], off offset:64
	global_load_dwordx4 v[56:59], v[24:25], off offset:384
	global_load_dwordx4 v[88:91], v[26:27], off offset:128
	global_load_dwordx4 v[60:63], v[24:25], off offset:448
	global_load_dwordx4 v[92:95], v[26:27], off offset:192
	s_add_u32 s24, s24, 0x200
	s_addc_u32 s25, s25, 0
	s_cmpk_eq_i32 s24, 0x800
	s_waitcnt vmcnt(14)
	v_mfma_f32_16x16x32_bf16 v[0:3], v[32:35], v[64:67], v[0:3]
	s_waitcnt vmcnt(12)
	v_mfma_f32_16x16x32_bf16 v[0:3], v[36:39], v[68:71], v[0:3]
	s_waitcnt vmcnt(10)
	v_mfma_f32_16x16x32_bf16 v[0:3], v[40:43], v[72:75], v[0:3]
	s_waitcnt vmcnt(8)
	v_mfma_f32_16x16x32_bf16 v[0:3], v[44:47], v[76:79], v[0:3]
	s_waitcnt vmcnt(6)
	v_mfma_f32_16x16x32_bf16 v[0:3], v[48:51], v[80:83], v[0:3]
	s_waitcnt vmcnt(4)
	v_mfma_f32_16x16x32_bf16 v[0:3], v[52:55], v[84:87], v[0:3]
	s_waitcnt vmcnt(2)
	v_mfma_f32_16x16x32_bf16 v[0:3], v[56:59], v[88:91], v[0:3]
	s_waitcnt vmcnt(0)
	v_mfma_f32_16x16x32_bf16 v[0:3], v[60:63], v[92:95], v[0:3]
	s_cbranch_scc0 .LBB0_1563
	s_lshl_b32 s17, s0, 4
	s_and_b32 s17, s17, 0x3f0
	v_add_u32_e32 v8, s7, v14
	v_or_b32_e32 v16, s17, v12
	v_ashrrev_i32_e32 v9, 31, v8
	v_lshlrev_b64 v[10:11], 12, v[8:9]
	v_lshlrev_b32_e32 v9, 2, v16
	v_or_b32_e32 v10, v10, v9
	v_lshl_add_u64 v[16:17], s[2:3], 0, v[10:11]
	global_load_dword v16, v[16:17], off
	v_readlane_b32 s24, v253, 8
	v_readlane_b32 s25, v253, 9
	s_brev_b32 s7, 32
	s_waitcnt vmcnt(0)
	v_fmamk_f32 v0, v16, 0x3fd744fd, v0
	v_lshl_add_u64 v[10:11], s[24:25], 0, v[10:11]
	v_add_co_u32_e32 v10, vcc, 0x4000000, v10
	s_nop 1
	v_addc_co_u32_e32 v11, vcc, 0, v11, vcc
	global_store_dword v[10:11], v0, off
	v_or_b32_e32 v10, 1, v8
	v_ashrrev_i32_e32 v11, 31, v10
	v_lshlrev_b64 v[10:11], 12, v[10:11]
	v_or_b32_e32 v10, v10, v9
	v_lshl_add_u64 v[16:17], s[2:3], 0, v[10:11]
	global_load_dword v0, v[16:17], off
	s_waitcnt vmcnt(0)
	v_fmamk_f32 v16, v0, 0x3fd744fd, v1
	v_lshl_add_u64 v[0:1], s[24:25], 0, v[10:11]
	v_add_co_u32_e32 v0, vcc, s7, v0
	s_nop 1
	v_addc_co_u32_e32 v1, vcc, 0, v1, vcc
	global_store_dword v[0:1], v16, off
	v_or_b32_e32 v0, 2, v8
	v_ashrrev_i32_e32 v1, 31, v0
	v_lshlrev_b64 v[0:1], 12, v[0:1]
	v_or_b32_e32 v0, v0, v9
	v_lshl_add_u64 v[10:11], s[2:3], 0, v[0:1]
	global_load_dword v10, v[10:11], off
	v_lshl_add_u64 v[0:1], s[24:25], 0, v[0:1]
	v_add_co_u32_e32 v0, vcc, s7, v0
	v_readlane_b32 s7, v254, 54
	s_nop 0
	v_addc_co_u32_e32 v1, vcc, 0, v1, vcc
	s_add_i32 s5, s5, s7
	s_waitcnt vmcnt(0)
	v_fmamk_f32 v2, v10, 0x3fd744fd, v2
	global_store_dword v[0:1], v2, off
	v_or_b32_e32 v0, 3, v8
	v_ashrrev_i32_e32 v1, 31, v0
	v_lshlrev_b64 v[0:1], 12, v[0:1]
	v_or_b32_e32 v0, v0, v9
	v_lshl_add_u64 v[8:9], s[2:3], 0, v[0:1]
	global_load_dword v2, v[8:9], off
	v_lshl_add_u64 v[0:1], s[24:25], 0, v[0:1]
	v_readlane_b32 s24, v255, 13
	v_add_co_u32_e32 v0, vcc, 0x4000000, v0
	s_add_i32 s0, s0, s24
	s_nop 0
	v_addc_co_u32_e32 v1, vcc, 0, v1, vcc
	s_cmpk_gt_i32 s0, 0x3ff
	v_readlane_b32 s25, v255, 14
	s_waitcnt vmcnt(0)
	v_fmac_f32_e32 v3, 0x3fd744fd, v2
	global_store_dword v[0:1], v3, off
	s_cbranch_scc0 .LBB0_1562
